# fox unit epilogue: 8 gate loads hoisted (were load-wait-store serialized)
# speedup vs baseline: 1.0170x; 1.0032x over previous
; DI unsigned pk2(float lo, float hi) { unsigned r; asm volatile("v_cvt_pk_bf16_f32 %0, %1, %2" : "=v"(r) : "v"(lo), "v"(hi)); return r; }
; DI float bflo(unsigned u) { return __uint_as_float(u << 16); }
; DI float bfhi(unsigned u) { return __uint_as_float(u & 0xffff0000u); }
; DI float silu_f(float x) { return x * __builtin_amdgcn_rcpf(1.0f + __expf(-x)); }
; DI float shx(float v, int m, int lane) { return __int_as_float(__builtin_amdgcn_ds_bpermute((lane ^ m) << 2, __float_as_int(v))); }
; DI void fox_unit(const Params& p, int hf, int bl, int fh, int qb, unsigned char* shm, int tid, bool dry = false) {
;     ...
; #pragma unroll
;   for (int mi = 0; mi < 2; ++mi) {
;     float l = lsum[mi]; l += shx(l, 16, lane); l += shx(l, 32, lane);
;     const float inv = 1.0f / l;
;     bf16_t* gp = projb + (size_t)(qg0 + 16 * mi) * NP + C_FG + fh * 64 + 4 * fq;
; #pragma unroll
;     for (int d = 0; d < 4; ++d) {
;       const uint2 gv = *(const uint2*)(gp + 16 * d);
;       uint2 w;
;       w.x = pk2(o[mi][d][0] * inv * silu_f(bflo(gv.x)), o[mi][d][1] * inv * silu_f(bfhi(gv.x)));
;       w.y = pk2(o[mi][d][2] * inv * silu_f(bflo(gv.y)), o[mi][d][3] * inv * silu_f(bfhi(gv.y)));
;       if (!dry || inv == 1.2345e-30f) *(uint2*)(gp + 16 * d) = w;
;     }
;   }
.LBB0_620:
	ds_bpermute_b32 v0, v204, v128
	v_mov_b32_e32 v27, v161
	s_mov_b64 s[6:7], 0x3000
	s_movk_i32 s4, 0x3000
	s_waitcnt lgkmcnt(0)
	v_add_f32_e32 v0, v128, v0
	ds_bpermute_b32 v1, v169, v0
	s_waitcnt lgkmcnt(0)
	v_add_f32_e32 v0, v0, v1
	v_div_scale_f32 v1, s[0:1], v0, v0, 1.0
	v_rcp_f32_e32 v2, v1
	s_nop 0
	v_fma_f32 v3, -v1, v2, 1.0
	v_fmac_f32_e32 v2, v3, v2
	v_div_scale_f32 v3, vcc, 1.0, v0, 1.0
	v_mul_f32_e32 v4, v3, v2
	v_fma_f32 v5, -v1, v4, v3
	v_fmac_f32_e32 v4, v5, v2
	v_fma_f32 v1, -v1, v4, v3
	v_div_fmas_f32 v1, v1, v2, v4
	v_div_fixup_f32 v6, v1, v0, 1.0
	v_lshl_add_u64 v[2:3], v[126:127], 0, s[2:3]
	v_lshlrev_b64 v[0:1], 1, v[26:27]
	v_lshl_add_u64 v[4:5], v[2:3], 0, v[0:1]
	v_lshl_add_u64 v[2:3], v[4:5], 0, s[6:7]
	global_load_dwordx2 v[40:41], v[2:3], off
	global_load_dwordx2 v[42:43], v[2:3], off offset:32
	global_load_dwordx2 v[44:45], v[2:3], off offset:64
	global_load_dwordx2 v[46:47], v[2:3], off offset:96
	v_lshl_add_u64 v[58:59], v[108:109], 0, s[2:3]
	v_lshl_add_u64 v[58:59], v[58:59], 0, v[0:1]
	v_lshl_add_u64 v[58:59], v[58:59], 0, s[6:7]
	global_load_dwordx2 v[48:49], v[58:59], off
	global_load_dwordx2 v[50:51], v[58:59], off offset:32
	global_load_dwordx2 v[52:53], v[58:59], off offset:64
	global_load_dwordx2 v[54:55], v[58:59], off offset:96
	v_add_co_u32_e32 v4, vcc, s4, v4
	v_mul_f32_e32 v7, v142, v6
	s_nop 0
	v_addc_co_u32_e32 v5, vcc, 0, v5, vcc
	s_waitcnt vmcnt(7)
	v_mov_b32_e32 v8, v40
	v_mov_b32_e32 v9, v41
	v_lshlrev_b32_e32 v10, 16, v8
	v_mul_f32_e32 v11, 0xbfb8aa3b, v10
	v_exp_f32_e32 v11, v11
	v_and_b32_e32 v8, 0xffff0000, v8
	v_add_f32_e32 v11, 1.0, v11
	v_rcp_f32_e32 v11, v11
	s_nop 0
	v_mul_f32_e32 v10, v11, v10
	v_mul_f32_e32 v11, 0xbfb8aa3b, v8
	v_exp_f32_e32 v11, v11
	v_mul_f32_e32 v7, v7, v10
	v_mul_f32_e32 v10, v143, v6
	v_add_f32_e32 v11, 1.0, v11
	v_rcp_f32_e32 v11, v11
	s_nop 0
	v_mul_f32_e32 v8, v11, v8
	v_mul_f32_e32 v8, v10, v8
	v_lshlrev_b32_e32 v10, 16, v9
	v_mul_f32_e32 v11, 0xbfb8aa3b, v10
	v_exp_f32_e32 v11, v11
	v_and_b32_e32 v9, 0xffff0000, v9
	v_cvt_pk_bf16_f32 v8, v7, v8
	v_mul_f32_e32 v7, v144, v6
	v_add_f32_e32 v11, 1.0, v11
	v_rcp_f32_e32 v11, v11
	s_nop 0
	v_mul_f32_e32 v10, v11, v10
	v_mul_f32_e32 v11, 0xbfb8aa3b, v9
	v_exp_f32_e32 v11, v11
	v_mul_f32_e32 v7, v7, v10
	v_mul_f32_e32 v10, v145, v6
	v_add_f32_e32 v11, 1.0, v11
	v_rcp_f32_e32 v11, v11
	s_nop 0
	v_mul_f32_e32 v9, v11, v9
	v_mul_f32_e32 v9, v10, v9
	v_cvt_pk_bf16_f32 v9, v7, v9
	global_store_dwordx2 v[4:5], v[8:9], off
	v_mul_f32_e32 v7, v138, v6
	s_waitcnt vmcnt(7)
	v_mov_b32_e32 v4, v42
	v_mov_b32_e32 v5, v43
	v_lshlrev_b32_e32 v8, 16, v4
	v_mul_f32_e32 v9, 0xbfb8aa3b, v8
	v_exp_f32_e32 v9, v9
	v_and_b32_e32 v4, 0xffff0000, v4
	v_add_f32_e32 v9, 1.0, v9
	v_rcp_f32_e32 v9, v9
	s_nop 0
	v_mul_f32_e32 v8, v9, v8
	v_mul_f32_e32 v9, 0xbfb8aa3b, v4
	v_exp_f32_e32 v9, v9
	v_mul_f32_e32 v7, v7, v8
	v_mul_f32_e32 v8, v139, v6
	v_add_f32_e32 v9, 1.0, v9
	v_rcp_f32_e32 v9, v9
	s_nop 0
	v_mul_f32_e32 v4, v9, v4
	v_mul_f32_e32 v4, v8, v4
	v_lshlrev_b32_e32 v8, 16, v5
	v_mul_f32_e32 v9, 0xbfb8aa3b, v8
	v_exp_f32_e32 v9, v9
	v_and_b32_e32 v5, 0xffff0000, v5
	v_cvt_pk_bf16_f32 v4, v7, v4
	v_mul_f32_e32 v7, v140, v6
	v_add_f32_e32 v9, 1.0, v9
	v_rcp_f32_e32 v9, v9
	s_nop 0
	v_mul_f32_e32 v8, v9, v8
	v_mul_f32_e32 v9, 0xbfb8aa3b, v5
	v_exp_f32_e32 v9, v9
	v_mul_f32_e32 v7, v7, v8
	v_mul_f32_e32 v8, v141, v6
	v_add_f32_e32 v9, 1.0, v9
	v_rcp_f32_e32 v9, v9
	s_nop 0
	v_mul_f32_e32 v5, v9, v5
	v_mul_f32_e32 v5, v8, v5
	v_cvt_pk_bf16_f32 v5, v7, v5
	global_store_dwordx2 v[2:3], v[4:5], off offset:32
	v_mul_f32_e32 v7, v134, v6
	s_waitcnt vmcnt(7)
	v_mov_b32_e32 v4, v44
	v_mov_b32_e32 v5, v45
	v_lshlrev_b32_e32 v8, 16, v4
	v_mul_f32_e32 v9, 0xbfb8aa3b, v8
	v_exp_f32_e32 v9, v9
	v_and_b32_e32 v4, 0xffff0000, v4
	v_add_f32_e32 v9, 1.0, v9
	v_rcp_f32_e32 v9, v9
	s_nop 0
	v_mul_f32_e32 v8, v9, v8
	v_mul_f32_e32 v9, 0xbfb8aa3b, v4
	v_exp_f32_e32 v9, v9
	v_mul_f32_e32 v7, v7, v8
	v_mul_f32_e32 v8, v135, v6
	v_add_f32_e32 v9, 1.0, v9
	v_rcp_f32_e32 v9, v9
	s_nop 0
	v_mul_f32_e32 v4, v9, v4
	v_mul_f32_e32 v4, v8, v4
	v_lshlrev_b32_e32 v8, 16, v5
	v_mul_f32_e32 v9, 0xbfb8aa3b, v8
	v_exp_f32_e32 v9, v9
	v_and_b32_e32 v5, 0xffff0000, v5
	v_cvt_pk_bf16_f32 v4, v7, v4
	v_mul_f32_e32 v7, v136, v6
	v_add_f32_e32 v9, 1.0, v9
	v_rcp_f32_e32 v9, v9
	s_nop 0
	v_mul_f32_e32 v8, v9, v8
	v_mul_f32_e32 v9, 0xbfb8aa3b, v5
	v_exp_f32_e32 v9, v9
	v_mul_f32_e32 v7, v7, v8
	v_mul_f32_e32 v8, v137, v6
	v_add_f32_e32 v9, 1.0, v9
	v_rcp_f32_e32 v9, v9
	s_nop 0
	v_mul_f32_e32 v5, v9, v5
	v_mul_f32_e32 v5, v8, v5
	v_cvt_pk_bf16_f32 v5, v7, v5
	global_store_dwordx2 v[2:3], v[4:5], off offset:64
	v_mul_f32_e32 v7, v130, v6
	s_waitcnt vmcnt(7)
	v_mov_b32_e32 v4, v46
	v_mov_b32_e32 v5, v47
	v_lshlrev_b32_e32 v8, 16, v4
	v_mul_f32_e32 v9, 0xbfb8aa3b, v8
	v_exp_f32_e32 v9, v9
	v_and_b32_e32 v4, 0xffff0000, v4
	v_add_f32_e32 v9, 1.0, v9
	v_rcp_f32_e32 v9, v9
	s_nop 0
	v_mul_f32_e32 v8, v9, v8
	v_mul_f32_e32 v9, 0xbfb8aa3b, v4
	v_exp_f32_e32 v9, v9
	v_mul_f32_e32 v7, v7, v8
	v_mul_f32_e32 v8, v131, v6
	v_add_f32_e32 v9, 1.0, v9
	v_rcp_f32_e32 v9, v9
	s_nop 0
	v_mul_f32_e32 v4, v9, v4
	v_mul_f32_e32 v4, v8, v4
	v_lshlrev_b32_e32 v8, 16, v5
	v_mul_f32_e32 v9, 0xbfb8aa3b, v8
	v_exp_f32_e32 v9, v9
	v_cvt_pk_bf16_f32 v4, v7, v4
	v_mul_f32_e32 v7, v132, v6
	v_and_b32_e32 v5, 0xffff0000, v5
	v_add_f32_e32 v9, 1.0, v9
	v_rcp_f32_e32 v9, v9
	v_mul_f32_e32 v6, v133, v6
	v_mul_f32_e32 v8, v9, v8
	v_mul_f32_e32 v7, v7, v8
	v_mul_f32_e32 v8, 0xbfb8aa3b, v5
	v_exp_f32_e32 v8, v8
	s_nop 0
	v_add_f32_e32 v8, 1.0, v8
	v_rcp_f32_e32 v8, v8
	s_nop 0
	v_mul_f32_e32 v5, v8, v5
	v_mul_f32_e32 v5, v6, v5
	v_cvt_pk_bf16_f32 v5, v7, v5
	global_store_dwordx2 v[2:3], v[4:5], off offset:96
	ds_bpermute_b32 v2, v204, v129
	s_waitcnt lgkmcnt(0)
; DI unsigned pk2(float lo, float hi) { unsigned r; asm volatile("v_cvt_pk_bf16_f32 %0, %1, %2" : "=v"(r) : "v"(lo), "v"(hi)); return r; }
; DI float bflo(unsigned u) { return __uint_as_float(u << 16); }
; DI float bfhi(unsigned u) { return __uint_as_float(u & 0xffff0000u); }
; DI float silu_f(float x) { return x * __builtin_amdgcn_rcpf(1.0f + __expf(-x)); }
; DI float shx(float v, int m, int lane) { return __int_as_float(__builtin_amdgcn_ds_bpermute((lane ^ m) << 2, __float_as_int(v))); }
; DI void fox_unit(const Params& p, int hf, int bl, int fh, int qb, unsigned char* shm, int tid, bool dry = false) {
;     ...
; #pragma unroll
;   for (int mi = 0; mi < 2; ++mi) {
;     float l = lsum[mi]; l += shx(l, 16, lane); l += shx(l, 32, lane);
;     const float inv = 1.0f / l;
;     bf16_t* gp = projb + (size_t)(qg0 + 16 * mi) * NP + C_FG + fh * 64 + 4 * fq;
; #pragma unroll
;     for (int d = 0; d < 4; ++d) {
;       const uint2 gv = *(const uint2*)(gp + 16 * d);
;       uint2 w;
;       w.x = pk2(o[mi][d][0] * inv * silu_f(bflo(gv.x)), o[mi][d][1] * inv * silu_f(bfhi(gv.x)));
;       w.y = pk2(o[mi][d][2] * inv * silu_f(bflo(gv.y)), o[mi][d][3] * inv * silu_f(bfhi(gv.y)));
;       if (!dry || inv == 1.2345e-30f) *(uint2*)(gp + 16 * d) = w;
;     }
;   }
	v_add_f32_e32 v2, v129, v2
	ds_bpermute_b32 v3, v169, v2
	s_waitcnt lgkmcnt(0)
	v_add_f32_e32 v2, v2, v3
	v_div_scale_f32 v3, s[0:1], v2, v2, 1.0
	v_rcp_f32_e32 v4, v3
	s_nop 0
	v_fma_f32 v5, -v3, v4, 1.0
	v_fmac_f32_e32 v4, v5, v4
	v_div_scale_f32 v5, vcc, 1.0, v2, 1.0
	v_mul_f32_e32 v6, v5, v4
	v_fma_f32 v7, -v3, v6, v5
	v_fmac_f32_e32 v6, v7, v4
	v_fma_f32 v3, -v3, v6, v5
	v_div_fmas_f32 v3, v3, v4, v6
	v_div_fixup_f32 v4, v3, v2, 1.0
	v_lshl_add_u64 v[2:3], v[108:109], 0, s[2:3]
	v_lshl_add_u64 v[2:3], v[2:3], 0, v[0:1]
	v_lshl_add_u64 v[0:1], v[2:3], 0, s[6:7]
	v_add_co_u32_e32 v2, vcc, s4, v2
	v_mul_f32_e32 v5, v122, v4
	s_nop 0
	v_addc_co_u32_e32 v3, vcc, 0, v3, vcc
	v_readlane_b32 s6, v254, 55
	v_readlane_b32 s7, v254, 56
	s_waitcnt vmcnt(7)
	v_mov_b32_e32 v6, v48
	v_mov_b32_e32 v7, v49
	v_lshlrev_b32_e32 v8, 16, v6
	v_mul_f32_e32 v9, 0xbfb8aa3b, v8
	v_exp_f32_e32 v9, v9
	v_and_b32_e32 v6, 0xffff0000, v6
	v_add_f32_e32 v9, 1.0, v9
	v_rcp_f32_e32 v9, v9
	s_nop 0
	v_mul_f32_e32 v8, v9, v8
	v_mul_f32_e32 v9, 0xbfb8aa3b, v6
	v_exp_f32_e32 v9, v9
	v_mul_f32_e32 v5, v5, v8
	v_mul_f32_e32 v8, v123, v4
	v_add_f32_e32 v9, 1.0, v9
	v_rcp_f32_e32 v9, v9
	s_nop 0
	v_mul_f32_e32 v6, v9, v6
	v_mul_f32_e32 v6, v8, v6
	v_lshlrev_b32_e32 v8, 16, v7
	v_mul_f32_e32 v9, 0xbfb8aa3b, v8
	v_exp_f32_e32 v9, v9
	v_and_b32_e32 v7, 0xffff0000, v7
	v_cvt_pk_bf16_f32 v6, v5, v6
	v_mul_f32_e32 v5, v124, v4
	v_add_f32_e32 v9, 1.0, v9
	v_rcp_f32_e32 v9, v9
	s_nop 0
	v_mul_f32_e32 v8, v9, v8
	v_mul_f32_e32 v9, 0xbfb8aa3b, v7
	v_exp_f32_e32 v9, v9
	v_mul_f32_e32 v5, v5, v8
	v_mul_f32_e32 v8, v125, v4
	v_add_f32_e32 v9, 1.0, v9
	v_rcp_f32_e32 v9, v9
	s_nop 0
	v_mul_f32_e32 v7, v9, v7
	v_mul_f32_e32 v7, v8, v7
	v_cvt_pk_bf16_f32 v7, v5, v7
	global_store_dwordx2 v[2:3], v[6:7], off
	v_mul_f32_e32 v5, v118, v4
	s_waitcnt vmcnt(7)
	v_mov_b32_e32 v2, v50
	v_mov_b32_e32 v3, v51
	v_lshlrev_b32_e32 v6, 16, v2
	v_mul_f32_e32 v7, 0xbfb8aa3b, v6
	v_exp_f32_e32 v7, v7
	v_and_b32_e32 v2, 0xffff0000, v2
	v_add_f32_e32 v7, 1.0, v7
	v_rcp_f32_e32 v7, v7
	s_nop 0
	v_mul_f32_e32 v6, v7, v6
	v_mul_f32_e32 v7, 0xbfb8aa3b, v2
	v_exp_f32_e32 v7, v7
	v_mul_f32_e32 v5, v5, v6
	v_mul_f32_e32 v6, v119, v4
	v_add_f32_e32 v7, 1.0, v7
	v_rcp_f32_e32 v7, v7
	s_nop 0
	v_mul_f32_e32 v2, v7, v2
	v_mul_f32_e32 v2, v6, v2
	v_lshlrev_b32_e32 v6, 16, v3
	v_mul_f32_e32 v7, 0xbfb8aa3b, v6
	v_exp_f32_e32 v7, v7
	v_and_b32_e32 v3, 0xffff0000, v3
	v_cvt_pk_bf16_f32 v2, v5, v2
	v_mul_f32_e32 v5, v120, v4
	v_add_f32_e32 v7, 1.0, v7
	v_rcp_f32_e32 v7, v7
	s_nop 0
	v_mul_f32_e32 v6, v7, v6
	v_mul_f32_e32 v7, 0xbfb8aa3b, v3
	v_exp_f32_e32 v7, v7
	v_mul_f32_e32 v5, v5, v6
	v_mul_f32_e32 v6, v121, v4
	v_add_f32_e32 v7, 1.0, v7
	v_rcp_f32_e32 v7, v7
	s_nop 0
	v_mul_f32_e32 v3, v7, v3
	v_mul_f32_e32 v3, v6, v3
	v_cvt_pk_bf16_f32 v3, v5, v3
	global_store_dwordx2 v[0:1], v[2:3], off offset:32
	v_mul_f32_e32 v5, v114, v4
	s_waitcnt vmcnt(7)
	v_mov_b32_e32 v2, v52
	v_mov_b32_e32 v3, v53
	v_lshlrev_b32_e32 v6, 16, v2
	v_mul_f32_e32 v7, 0xbfb8aa3b, v6
	v_exp_f32_e32 v7, v7
	v_and_b32_e32 v2, 0xffff0000, v2
	v_add_f32_e32 v7, 1.0, v7
	v_rcp_f32_e32 v7, v7
	s_nop 0
	v_mul_f32_e32 v6, v7, v6
	v_mul_f32_e32 v7, 0xbfb8aa3b, v2
	v_exp_f32_e32 v7, v7
	v_mul_f32_e32 v5, v5, v6
	v_mul_f32_e32 v6, v115, v4
	v_add_f32_e32 v7, 1.0, v7
	v_rcp_f32_e32 v7, v7
	s_nop 0
	v_mul_f32_e32 v2, v7, v2
	v_mul_f32_e32 v2, v6, v2
	v_lshlrev_b32_e32 v6, 16, v3
	v_mul_f32_e32 v7, 0xbfb8aa3b, v6
	v_exp_f32_e32 v7, v7
	v_and_b32_e32 v3, 0xffff0000, v3
	v_cvt_pk_bf16_f32 v2, v5, v2
	v_mul_f32_e32 v5, v116, v4
	v_add_f32_e32 v7, 1.0, v7
	v_rcp_f32_e32 v7, v7
	s_nop 0
	v_mul_f32_e32 v6, v7, v6
	v_mul_f32_e32 v7, 0xbfb8aa3b, v3
	v_exp_f32_e32 v7, v7
	v_mul_f32_e32 v5, v5, v6
	v_mul_f32_e32 v6, v117, v4
	v_add_f32_e32 v7, 1.0, v7
	v_rcp_f32_e32 v7, v7
	s_nop 0
	v_mul_f32_e32 v3, v7, v3
	v_mul_f32_e32 v3, v6, v3
	v_cvt_pk_bf16_f32 v3, v5, v3
	global_store_dwordx2 v[0:1], v[2:3], off offset:64
	v_mul_f32_e32 v5, v110, v4
	s_waitcnt vmcnt(7)
	v_mov_b32_e32 v2, v54
	v_mov_b32_e32 v3, v55
	v_lshlrev_b32_e32 v6, 16, v2
	v_mul_f32_e32 v7, 0xbfb8aa3b, v6
	v_exp_f32_e32 v7, v7
	v_and_b32_e32 v2, 0xffff0000, v2
	v_add_f32_e32 v7, 1.0, v7
	v_rcp_f32_e32 v7, v7
	s_nop 0
	v_mul_f32_e32 v6, v7, v6
	v_mul_f32_e32 v7, 0xbfb8aa3b, v2
	v_exp_f32_e32 v7, v7
	v_mul_f32_e32 v5, v5, v6
	v_mul_f32_e32 v6, v111, v4
	v_add_f32_e32 v7, 1.0, v7
	v_rcp_f32_e32 v7, v7
	s_nop 0
	v_mul_f32_e32 v2, v7, v2
	v_mul_f32_e32 v2, v6, v2
	v_lshlrev_b32_e32 v6, 16, v3
	v_mul_f32_e32 v7, 0xbfb8aa3b, v6
	v_exp_f32_e32 v7, v7
	v_cvt_pk_bf16_f32 v2, v5, v2
	v_mul_f32_e32 v5, v112, v4
	v_and_b32_e32 v3, 0xffff0000, v3
	v_add_f32_e32 v7, 1.0, v7
	v_rcp_f32_e32 v7, v7
	v_mul_f32_e32 v4, v113, v4
	v_mul_f32_e32 v6, v7, v6
	v_mul_f32_e32 v5, v5, v6
	v_mul_f32_e32 v6, 0xbfb8aa3b, v3
	v_exp_f32_e32 v6, v6
	s_nop 0
	v_add_f32_e32 v6, 1.0, v6
	v_rcp_f32_e32 v6, v6
	s_nop 0
	v_mul_f32_e32 v3, v6, v3
	v_mul_f32_e32 v3, v4, v3
	v_cvt_pk_bf16_f32 v3, v5, v3
	global_store_dwordx2 v[0:1], v[2:3], off offset:96
	v_mov_b32_e32 v162, 0x358637bd
	v_mov_b32_e32 v168, 0x3f317218
	v_mov_b64_e32 v[170:171], 0xff
	v_mov_b32_e32 v195, 0x3ecc95a3
	v_mov_b64_e32 v[196:197], 0x6bf
	v_mov_b32_e32 v198, 0x7f800000
	v_mov_b32_e32 v199, 0x7fc00000

; DI unsigned pk2(float lo, float hi) { unsigned r; asm volatile("v_cvt_pk_bf16_f32 %0, %1, %2" : "=v"(r) : "v"(lo), "v"(hi)); return r; }
; DI float bflo(unsigned u) { return __uint_as_float(u << 16); }
; DI float bfhi(unsigned u) { return __uint_as_float(u & 0xffff0000u); }
; DI float silu_f(float x) { return x * __builtin_amdgcn_rcpf(1.0f + __expf(-x)); }
; DI float shx(float v, int m, int lane) { return __int_as_float(__builtin_amdgcn_ds_bpermute((lane ^ m) << 2, __float_as_int(v))); }
; DI void fox_unit(const Params& p, int hf, int bl, int fh, int qb, unsigned char* shm, int tid, bool dry = false) {
;     ...
; #pragma unroll
;   for (int mi = 0; mi < 2; ++mi) {
;     float l = lsum[mi]; l += shx(l, 16, lane); l += shx(l, 32, lane);
;     const float inv = 1.0f / l;
;     bf16_t* gp = projb + (size_t)(qg0 + 16 * mi) * NP + C_FG + fh * 64 + 4 * fq;
; #pragma unroll
;     for (int d = 0; d < 4; ++d) {
;       const uint2 gv = *(const uint2*)(gp + 16 * d);
;       uint2 w;
;       w.x = pk2(o[mi][d][0] * inv * silu_f(bflo(gv.x)), o[mi][d][1] * inv * silu_f(bfhi(gv.x)));
;       w.y = pk2(o[mi][d][2] * inv * silu_f(bflo(gv.y)), o[mi][d][3] * inv * silu_f(bfhi(gv.y)));
;       if (!dry || inv == 1.2345e-30f) *(uint2*)(gp + 16 * d) = w;
;     }
;   }
.LBB0_635:
	ds_bpermute_b32 v0, v204, v128
	v_mov_b32_e32 v27, v161
	s_mov_b64 s[6:7], 0x3000
	s_movk_i32 s4, 0x3000
	s_waitcnt lgkmcnt(0)
	v_add_f32_e32 v0, v128, v0
	ds_bpermute_b32 v1, v169, v0
	s_waitcnt lgkmcnt(0)
	v_add_f32_e32 v0, v0, v1
	v_div_scale_f32 v1, s[0:1], v0, v0, 1.0
	v_rcp_f32_e32 v2, v1
	s_nop 0
	v_fma_f32 v3, -v1, v2, 1.0
	v_fmac_f32_e32 v2, v3, v2
	v_div_scale_f32 v3, vcc, 1.0, v0, 1.0
	v_mul_f32_e32 v4, v3, v2
	v_fma_f32 v5, -v1, v4, v3
	v_fmac_f32_e32 v4, v5, v2
	v_fma_f32 v1, -v1, v4, v3
	v_div_fmas_f32 v1, v1, v2, v4
	v_div_fixup_f32 v6, v1, v0, 1.0
	v_lshl_add_u64 v[2:3], v[126:127], 0, s[2:3]
	v_lshlrev_b64 v[0:1], 1, v[26:27]
	v_lshl_add_u64 v[4:5], v[2:3], 0, v[0:1]
	v_lshl_add_u64 v[2:3], v[4:5], 0, s[6:7]
	global_load_dwordx2 v[40:41], v[2:3], off
	global_load_dwordx2 v[42:43], v[2:3], off offset:32
	global_load_dwordx2 v[44:45], v[2:3], off offset:64
	global_load_dwordx2 v[46:47], v[2:3], off offset:96
	v_lshl_add_u64 v[58:59], v[108:109], 0, s[2:3]
	v_lshl_add_u64 v[58:59], v[58:59], 0, v[0:1]
	v_lshl_add_u64 v[58:59], v[58:59], 0, s[6:7]
	global_load_dwordx2 v[48:49], v[58:59], off
	global_load_dwordx2 v[50:51], v[58:59], off offset:32
	global_load_dwordx2 v[52:53], v[58:59], off offset:64
	global_load_dwordx2 v[54:55], v[58:59], off offset:96
	v_add_co_u32_e32 v4, vcc, s4, v4
	v_mul_f32_e32 v7, v142, v6
	s_nop 0
	v_addc_co_u32_e32 v5, vcc, 0, v5, vcc
	s_waitcnt vmcnt(7)
	v_mov_b32_e32 v8, v40
	v_mov_b32_e32 v9, v41
	v_lshlrev_b32_e32 v10, 16, v8
	v_mul_f32_e32 v11, 0xbfb8aa3b, v10
	v_exp_f32_e32 v11, v11
	v_and_b32_e32 v8, 0xffff0000, v8
	v_add_f32_e32 v11, 1.0, v11
	v_rcp_f32_e32 v11, v11
	s_nop 0
	v_mul_f32_e32 v10, v11, v10
	v_mul_f32_e32 v11, 0xbfb8aa3b, v8
	v_exp_f32_e32 v11, v11
	v_mul_f32_e32 v7, v7, v10
	v_mul_f32_e32 v10, v143, v6
	v_add_f32_e32 v11, 1.0, v11
	v_rcp_f32_e32 v11, v11
	s_nop 0
	v_mul_f32_e32 v8, v11, v8
	v_mul_f32_e32 v8, v10, v8
	v_lshlrev_b32_e32 v10, 16, v9
	v_mul_f32_e32 v11, 0xbfb8aa3b, v10
	v_exp_f32_e32 v11, v11
	v_and_b32_e32 v9, 0xffff0000, v9
	v_cvt_pk_bf16_f32 v8, v7, v8
	v_mul_f32_e32 v7, v144, v6
	v_add_f32_e32 v11, 1.0, v11
	v_rcp_f32_e32 v11, v11
	s_nop 0
	v_mul_f32_e32 v10, v11, v10
	v_mul_f32_e32 v11, 0xbfb8aa3b, v9
	v_exp_f32_e32 v11, v11
	v_mul_f32_e32 v7, v7, v10
	v_mul_f32_e32 v10, v145, v6
	v_add_f32_e32 v11, 1.0, v11
	v_rcp_f32_e32 v11, v11
	s_nop 0
	v_mul_f32_e32 v9, v11, v9
	v_mul_f32_e32 v9, v10, v9
	v_cvt_pk_bf16_f32 v9, v7, v9
	global_store_dwordx2 v[4:5], v[8:9], off
	v_mul_f32_e32 v7, v138, v6
	s_waitcnt vmcnt(7)
	v_mov_b32_e32 v4, v42
	v_mov_b32_e32 v5, v43
	v_lshlrev_b32_e32 v8, 16, v4
	v_mul_f32_e32 v9, 0xbfb8aa3b, v8
	v_exp_f32_e32 v9, v9
	v_and_b32_e32 v4, 0xffff0000, v4
	v_add_f32_e32 v9, 1.0, v9
	v_rcp_f32_e32 v9, v9
	s_nop 0
	v_mul_f32_e32 v8, v9, v8
	v_mul_f32_e32 v9, 0xbfb8aa3b, v4
	v_exp_f32_e32 v9, v9
	v_mul_f32_e32 v7, v7, v8
	v_mul_f32_e32 v8, v139, v6
	v_add_f32_e32 v9, 1.0, v9
	v_rcp_f32_e32 v9, v9
	s_nop 0
	v_mul_f32_e32 v4, v9, v4
	v_mul_f32_e32 v4, v8, v4
	v_lshlrev_b32_e32 v8, 16, v5
	v_mul_f32_e32 v9, 0xbfb8aa3b, v8
	v_exp_f32_e32 v9, v9
	v_and_b32_e32 v5, 0xffff0000, v5
	v_cvt_pk_bf16_f32 v4, v7, v4
	v_mul_f32_e32 v7, v140, v6
	v_add_f32_e32 v9, 1.0, v9
	v_rcp_f32_e32 v9, v9
	s_nop 0
	v_mul_f32_e32 v8, v9, v8
	v_mul_f32_e32 v9, 0xbfb8aa3b, v5
	v_exp_f32_e32 v9, v9
	v_mul_f32_e32 v7, v7, v8
	v_mul_f32_e32 v8, v141, v6
	v_add_f32_e32 v9, 1.0, v9
	v_rcp_f32_e32 v9, v9
	s_nop 0
	v_mul_f32_e32 v5, v9, v5
	v_mul_f32_e32 v5, v8, v5
	v_cvt_pk_bf16_f32 v5, v7, v5
	global_store_dwordx2 v[2:3], v[4:5], off offset:32
	v_mul_f32_e32 v7, v134, v6
	s_waitcnt vmcnt(7)
	v_mov_b32_e32 v4, v44
	v_mov_b32_e32 v5, v45
	v_lshlrev_b32_e32 v8, 16, v4
	v_mul_f32_e32 v9, 0xbfb8aa3b, v8
	v_exp_f32_e32 v9, v9
	v_and_b32_e32 v4, 0xffff0000, v4
	v_add_f32_e32 v9, 1.0, v9
	v_rcp_f32_e32 v9, v9
	s_nop 0
	v_mul_f32_e32 v8, v9, v8
	v_mul_f32_e32 v9, 0xbfb8aa3b, v4
	v_exp_f32_e32 v9, v9
	v_mul_f32_e32 v7, v7, v8
	v_mul_f32_e32 v8, v135, v6
	v_add_f32_e32 v9, 1.0, v9
	v_rcp_f32_e32 v9, v9
	s_nop 0
	v_mul_f32_e32 v4, v9, v4
	v_mul_f32_e32 v4, v8, v4
	v_lshlrev_b32_e32 v8, 16, v5
	v_mul_f32_e32 v9, 0xbfb8aa3b, v8
	v_exp_f32_e32 v9, v9
	v_and_b32_e32 v5, 0xffff0000, v5
	v_cvt_pk_bf16_f32 v4, v7, v4
	v_mul_f32_e32 v7, v136, v6
	v_add_f32_e32 v9, 1.0, v9
	v_rcp_f32_e32 v9, v9
	s_nop 0
	v_mul_f32_e32 v8, v9, v8
	v_mul_f32_e32 v9, 0xbfb8aa3b, v5
	v_exp_f32_e32 v9, v9
	v_mul_f32_e32 v7, v7, v8
	v_mul_f32_e32 v8, v137, v6
	v_add_f32_e32 v9, 1.0, v9
	v_rcp_f32_e32 v9, v9
	s_nop 0
	v_mul_f32_e32 v5, v9, v5
	v_mul_f32_e32 v5, v8, v5
	v_cvt_pk_bf16_f32 v5, v7, v5
	global_store_dwordx2 v[2:3], v[4:5], off offset:64
	v_mul_f32_e32 v7, v130, v6
	s_waitcnt vmcnt(7)
	v_mov_b32_e32 v4, v46
	v_mov_b32_e32 v5, v47
	v_lshlrev_b32_e32 v8, 16, v4
	v_mul_f32_e32 v9, 0xbfb8aa3b, v8
	v_exp_f32_e32 v9, v9
	v_and_b32_e32 v4, 0xffff0000, v4
	v_add_f32_e32 v9, 1.0, v9
	v_rcp_f32_e32 v9, v9
	s_nop 0
	v_mul_f32_e32 v8, v9, v8
	v_mul_f32_e32 v9, 0xbfb8aa3b, v4
	v_exp_f32_e32 v9, v9
	v_mul_f32_e32 v7, v7, v8
	v_mul_f32_e32 v8, v131, v6
	v_add_f32_e32 v9, 1.0, v9
	v_rcp_f32_e32 v9, v9
	s_nop 0
	v_mul_f32_e32 v4, v9, v4
	v_mul_f32_e32 v4, v8, v4
	v_lshlrev_b32_e32 v8, 16, v5
	v_mul_f32_e32 v9, 0xbfb8aa3b, v8
	v_exp_f32_e32 v9, v9
	v_cvt_pk_bf16_f32 v4, v7, v4
	v_mul_f32_e32 v7, v132, v6
	v_and_b32_e32 v5, 0xffff0000, v5
	v_add_f32_e32 v9, 1.0, v9
	v_rcp_f32_e32 v9, v9
	v_mul_f32_e32 v6, v133, v6
	v_mul_f32_e32 v8, v9, v8
	v_mul_f32_e32 v7, v7, v8
	v_mul_f32_e32 v8, 0xbfb8aa3b, v5
	v_exp_f32_e32 v8, v8
	s_nop 0
	v_add_f32_e32 v8, 1.0, v8
	v_rcp_f32_e32 v8, v8
	s_nop 0
	v_mul_f32_e32 v5, v8, v5
	v_mul_f32_e32 v5, v6, v5
	v_cvt_pk_bf16_f32 v5, v7, v5
	global_store_dwordx2 v[2:3], v[4:5], off offset:96
	ds_bpermute_b32 v2, v204, v129
	s_waitcnt lgkmcnt(0)
; DI unsigned pk2(float lo, float hi) { unsigned r; asm volatile("v_cvt_pk_bf16_f32 %0, %1, %2" : "=v"(r) : "v"(lo), "v"(hi)); return r; }
; DI float bflo(unsigned u) { return __uint_as_float(u << 16); }
; DI float bfhi(unsigned u) { return __uint_as_float(u & 0xffff0000u); }
; DI float silu_f(float x) { return x * __builtin_amdgcn_rcpf(1.0f + __expf(-x)); }
; DI float shx(float v, int m, int lane) { return __int_as_float(__builtin_amdgcn_ds_bpermute((lane ^ m) << 2, __float_as_int(v))); }
; DI void fox_unit(const Params& p, int hf, int bl, int fh, int qb, unsigned char* shm, int tid, bool dry = false) {
;     ...
; #pragma unroll
;   for (int mi = 0; mi < 2; ++mi) {
;     float l = lsum[mi]; l += shx(l, 16, lane); l += shx(l, 32, lane);
;     const float inv = 1.0f / l;
;     bf16_t* gp = projb + (size_t)(qg0 + 16 * mi) * NP + C_FG + fh * 64 + 4 * fq;
; #pragma unroll
;     for (int d = 0; d < 4; ++d) {
;       const uint2 gv = *(const uint2*)(gp + 16 * d);
;       uint2 w;
;       w.x = pk2(o[mi][d][0] * inv * silu_f(bflo(gv.x)), o[mi][d][1] * inv * silu_f(bfhi(gv.x)));
;       w.y = pk2(o[mi][d][2] * inv * silu_f(bflo(gv.y)), o[mi][d][3] * inv * silu_f(bfhi(gv.y)));
;       if (!dry || inv == 1.2345e-30f) *(uint2*)(gp + 16 * d) = w;
;     }
;   }
	v_add_f32_e32 v2, v129, v2
	ds_bpermute_b32 v3, v169, v2
	s_waitcnt lgkmcnt(0)
	v_add_f32_e32 v2, v2, v3
	v_div_scale_f32 v3, s[0:1], v2, v2, 1.0
	v_rcp_f32_e32 v4, v3
	s_nop 0
	v_fma_f32 v5, -v3, v4, 1.0
	v_fmac_f32_e32 v4, v5, v4
	v_div_scale_f32 v5, vcc, 1.0, v2, 1.0
	v_mul_f32_e32 v6, v5, v4
	v_fma_f32 v7, -v3, v6, v5
	v_fmac_f32_e32 v6, v7, v4
	v_fma_f32 v3, -v3, v6, v5
	v_div_fmas_f32 v3, v3, v4, v6
	v_div_fixup_f32 v4, v3, v2, 1.0
	v_lshl_add_u64 v[2:3], v[108:109], 0, s[2:3]
	v_lshl_add_u64 v[2:3], v[2:3], 0, v[0:1]
	v_lshl_add_u64 v[0:1], v[2:3], 0, s[6:7]
	v_add_co_u32_e32 v2, vcc, s4, v2
	v_mul_f32_e32 v5, v122, v4
	s_nop 0
	v_addc_co_u32_e32 v3, vcc, 0, v3, vcc
	s_waitcnt vmcnt(7)
	v_mov_b32_e32 v6, v48
	v_mov_b32_e32 v7, v49
	v_lshlrev_b32_e32 v8, 16, v6
	v_mul_f32_e32 v9, 0xbfb8aa3b, v8
	v_exp_f32_e32 v9, v9
	v_and_b32_e32 v6, 0xffff0000, v6
	v_add_f32_e32 v9, 1.0, v9
	v_rcp_f32_e32 v9, v9
	s_nop 0
	v_mul_f32_e32 v8, v9, v8
	v_mul_f32_e32 v9, 0xbfb8aa3b, v6
	v_exp_f32_e32 v9, v9
	v_mul_f32_e32 v5, v5, v8
	v_mul_f32_e32 v8, v123, v4
	v_add_f32_e32 v9, 1.0, v9
	v_rcp_f32_e32 v9, v9
	s_nop 0
	v_mul_f32_e32 v6, v9, v6
	v_mul_f32_e32 v6, v8, v6
	v_lshlrev_b32_e32 v8, 16, v7
	v_mul_f32_e32 v9, 0xbfb8aa3b, v8
	v_exp_f32_e32 v9, v9
	v_and_b32_e32 v7, 0xffff0000, v7
	v_cvt_pk_bf16_f32 v6, v5, v6
	v_mul_f32_e32 v5, v124, v4
	v_add_f32_e32 v9, 1.0, v9
	v_rcp_f32_e32 v9, v9
	s_nop 0
	v_mul_f32_e32 v8, v9, v8
	v_mul_f32_e32 v9, 0xbfb8aa3b, v7
	v_exp_f32_e32 v9, v9
	v_mul_f32_e32 v5, v5, v8
	v_mul_f32_e32 v8, v125, v4
	v_add_f32_e32 v9, 1.0, v9
	v_rcp_f32_e32 v9, v9
	s_nop 0
	v_mul_f32_e32 v7, v9, v7
	v_mul_f32_e32 v7, v8, v7
	v_cvt_pk_bf16_f32 v7, v5, v7
	global_store_dwordx2 v[2:3], v[6:7], off
	v_mul_f32_e32 v5, v118, v4
	s_waitcnt vmcnt(7)
	v_mov_b32_e32 v2, v50
	v_mov_b32_e32 v3, v51
	v_lshlrev_b32_e32 v6, 16, v2
	v_mul_f32_e32 v7, 0xbfb8aa3b, v6
	v_exp_f32_e32 v7, v7
	v_and_b32_e32 v2, 0xffff0000, v2
	v_add_f32_e32 v7, 1.0, v7
	v_rcp_f32_e32 v7, v7
	s_nop 0
	v_mul_f32_e32 v6, v7, v6
	v_mul_f32_e32 v7, 0xbfb8aa3b, v2
	v_exp_f32_e32 v7, v7
	v_mul_f32_e32 v5, v5, v6
	v_mul_f32_e32 v6, v119, v4
	v_add_f32_e32 v7, 1.0, v7
	v_rcp_f32_e32 v7, v7
	s_nop 0
	v_mul_f32_e32 v2, v7, v2
	v_mul_f32_e32 v2, v6, v2
	v_lshlrev_b32_e32 v6, 16, v3
	v_mul_f32_e32 v7, 0xbfb8aa3b, v6
	v_exp_f32_e32 v7, v7
	v_and_b32_e32 v3, 0xffff0000, v3
	v_cvt_pk_bf16_f32 v2, v5, v2
	v_mul_f32_e32 v5, v120, v4
	v_add_f32_e32 v7, 1.0, v7
	v_rcp_f32_e32 v7, v7
	s_nop 0
	v_mul_f32_e32 v6, v7, v6
	v_mul_f32_e32 v7, 0xbfb8aa3b, v3
	v_exp_f32_e32 v7, v7
	v_mul_f32_e32 v5, v5, v6
	v_mul_f32_e32 v6, v121, v4
	v_add_f32_e32 v7, 1.0, v7
	v_rcp_f32_e32 v7, v7
	s_nop 0
	v_mul_f32_e32 v3, v7, v3
	v_mul_f32_e32 v3, v6, v3
	v_cvt_pk_bf16_f32 v3, v5, v3
	global_store_dwordx2 v[0:1], v[2:3], off offset:32
	v_mul_f32_e32 v5, v114, v4
	s_waitcnt vmcnt(7)
	v_mov_b32_e32 v2, v52
	v_mov_b32_e32 v3, v53
	v_lshlrev_b32_e32 v6, 16, v2
	v_mul_f32_e32 v7, 0xbfb8aa3b, v6
	v_exp_f32_e32 v7, v7
	v_and_b32_e32 v2, 0xffff0000, v2
	v_add_f32_e32 v7, 1.0, v7
	v_rcp_f32_e32 v7, v7
	s_nop 0
	v_mul_f32_e32 v6, v7, v6
	v_mul_f32_e32 v7, 0xbfb8aa3b, v2
	v_exp_f32_e32 v7, v7
	v_mul_f32_e32 v5, v5, v6
	v_mul_f32_e32 v6, v115, v4
	v_add_f32_e32 v7, 1.0, v7
	v_rcp_f32_e32 v7, v7
	s_nop 0
	v_mul_f32_e32 v2, v7, v2
	v_mul_f32_e32 v2, v6, v2
	v_lshlrev_b32_e32 v6, 16, v3
	v_mul_f32_e32 v7, 0xbfb8aa3b, v6
	v_exp_f32_e32 v7, v7
	v_and_b32_e32 v3, 0xffff0000, v3
	v_cvt_pk_bf16_f32 v2, v5, v2
	v_mul_f32_e32 v5, v116, v4
	v_add_f32_e32 v7, 1.0, v7
	v_rcp_f32_e32 v7, v7
	s_nop 0
	v_mul_f32_e32 v6, v7, v6
	v_mul_f32_e32 v7, 0xbfb8aa3b, v3
	v_exp_f32_e32 v7, v7
	v_mul_f32_e32 v5, v5, v6
	v_mul_f32_e32 v6, v117, v4
	v_add_f32_e32 v7, 1.0, v7
	v_rcp_f32_e32 v7, v7
	s_nop 0
	v_mul_f32_e32 v3, v7, v3
	v_mul_f32_e32 v3, v6, v3
	v_cvt_pk_bf16_f32 v3, v5, v3
	global_store_dwordx2 v[0:1], v[2:3], off offset:64
	v_mul_f32_e32 v5, v110, v4
	s_waitcnt vmcnt(7)
	v_mov_b32_e32 v2, v54
	v_mov_b32_e32 v3, v55
	v_lshlrev_b32_e32 v6, 16, v2
	v_mul_f32_e32 v7, 0xbfb8aa3b, v6
	v_exp_f32_e32 v7, v7
	v_and_b32_e32 v2, 0xffff0000, v2
	v_add_f32_e32 v7, 1.0, v7
	v_rcp_f32_e32 v7, v7
	s_nop 0
	v_mul_f32_e32 v6, v7, v6
	v_mul_f32_e32 v7, 0xbfb8aa3b, v2
	v_exp_f32_e32 v7, v7
	v_mul_f32_e32 v5, v5, v6
	v_mul_f32_e32 v6, v111, v4
	v_add_f32_e32 v7, 1.0, v7
	v_rcp_f32_e32 v7, v7
	s_nop 0
	v_mul_f32_e32 v2, v7, v2
	v_mul_f32_e32 v2, v6, v2
	v_lshlrev_b32_e32 v6, 16, v3
	v_mul_f32_e32 v7, 0xbfb8aa3b, v6
	v_exp_f32_e32 v7, v7
	v_cvt_pk_bf16_f32 v2, v5, v2
	v_mul_f32_e32 v5, v112, v4
	v_and_b32_e32 v3, 0xffff0000, v3
	v_add_f32_e32 v7, 1.0, v7
	v_rcp_f32_e32 v7, v7
	v_mul_f32_e32 v4, v113, v4
	v_mul_f32_e32 v6, v7, v6
	v_mul_f32_e32 v5, v5, v6
	v_mul_f32_e32 v6, 0xbfb8aa3b, v3
	v_exp_f32_e32 v6, v6
	s_nop 0
	v_add_f32_e32 v6, 1.0, v6
	v_rcp_f32_e32 v6, v6
	s_nop 0
	v_mul_f32_e32 v3, v6, v3
	v_mul_f32_e32 v3, v4, v3
	v_cvt_pk_bf16_f32 v3, v5, v3
	global_store_dwordx2 v[0:1], v[2:3], off offset:96
	s_cbranch_execz .LBB0_501
	v_mov_b32_e32 v162, 0x358637bd
	v_mov_b32_e32 v168, 0x3f317218
	v_mov_b64_e32 v[170:171], 0xff
	v_mov_b32_e32 v195, 0x3ecc95a3
	v_mov_b64_e32 v[196:197], 0x6bf
	v_mov_b32_e32 v198, 0x7f800000
	v_mov_b32_e32 v199, 0x7fc00000
	s_branch .LBB0_572
